# P1: next-unit tile-scheduler scalar code moved from unit header into the peeled SP1 MFMA shadow
# speedup vs baseline: 1.0039x; 1.0039x over previous
.LBB0_381:
.LBB0_383:
	s_add_u32 s39, s82, 0x100
	s_addc_u32 s67, s83, 0
	s_mov_b32 s94, -2
	s_mov_b64 vcc, 0
	v_lshl_add_u64 v[132:133], s[4:5], 0, v[168:169]
	ds_read_b128 v[134:137], v199
	ds_read_b128 v[138:141], v200
	ds_read_b128 v[142:145], v201
	ds_read_b128 v[146:149], v202
	ds_read_b128 v[150:153], v203
	ds_read_b128 v[174:177], v204
	ds_read_b128 v[178:181], v205
	ds_read_b128 v[182:185], v206
	s_add_u32 s24, s4, vcc_lo
	s_addc_u32 s25, s5, vcc_hi
	s_add_u32 s24, s24, 0x100
	s_addc_u32 s25, s25, 0
	s_add_u32 s82, s39, vcc_lo
	s_addc_u32 s83, s67, vcc_hi
	s_cmpk_eq_i32 vcc_lo, 0x700
	s_cselect_b32 s87, s29, s83
	s_cselect_b32 s86, s38, s82
	s_cselect_b32 s83, s34, s25
	s_cselect_b32 s82, s35, s24
	v_lshl_add_u64 v[154:155], v[132:133], 0, vcc
	v_lshl_add_u64 v[250:251], v[154:155], 0, s[48:49]
	s_add_i32 m0, s79, 0x8000
	s_mov_b64 s[24:25], 0x20080
	ds_read_b128 v[218:221], v207
	ds_read_b128 v[222:225], v207 offset:2048
	ds_read_b128 v[226:229], v208
	ds_read_b128 v[230:233], v208 offset:2048
	ds_read_b128 v[234:237], v207 offset:4096
	ds_read_b128 v[238:241], v207 offset:6144
	ds_read_b128 v[242:245], v208 offset:4096
	ds_read_b128 v[246:249], v208 offset:6144
	global_load_lds_dwordx4 v[250:251], off
	v_lshl_add_u64 v[250:251], v[154:155], 0, s[24:25]
	s_add_i32 m0, s79, 0xa000
	s_mov_b64 s[24:25], 0x60080
	global_load_lds_dwordx4 v[250:251], off
	v_lshl_add_u64 v[250:251], v[154:155], 0, s[50:51]
	s_add_i32 m0, s79, 0xc000
	v_lshl_add_u64 v[154:155], v[154:155], 0, s[24:25]
	global_load_lds_dwordx4 v[250:251], off
	s_add_i32 m0, s79, 0xe000
	s_nop 0
	global_load_lds_dwordx4 v[154:155], off
	s_waitcnt vmcnt(16)
	s_waitcnt lgkmcnt(0)
	s_barrier
	s_cmp_lg_u32 s98, 0
	s_cbranch_scc1 .Lp1b_skip
	v_mbcnt_lo_u32_b32 v255, -1, 0
	v_mbcnt_hi_u32_b32 v255, -1, v255
	s_cmp_gt_i32 s96, 13
	s_cbranch_scc1 .Lp1b_gate
	s_lshl_b32 s100, s96, 10
	s_add_u32 s100, s90, s100
	s_addc_u32 s101, s91, 0
	v_lshlrev_b32_e32 v255, 4, v255
	s_branch .Lp1b_issue

.Lp1b_skip:
	v_mfma_f32_16x16x32_bf16 v[128:131], v[134:137], v[218:221], 0
	v_mfma_f32_16x16x32_bf16 v[128:131], v[138:141], v[226:229], v[128:131]
	s_add_i32 s0, s0, 1
	s_mul_i32 s8, s0, s3
	s_mul_hi_u32 s9, s0, s33
	s_add_i32 s9, s9, s8
	s_mul_i32 s8, s0, s33
	v_mfma_f32_16x16x32_bf16 v[112:115], v[134:137], v[222:225], 0
	v_mfma_f32_16x16x32_bf16 v[112:115], v[138:141], v[230:233], v[112:115]
	s_add_u32 s26, s8, s2
	s_addc_u32 s27, s9, s73
	v_cmp_lt_i64_e64 s[8:9], s[26:27], v[170:171]
	s_ashr_i32 s24, s26, 31
	s_lshr_b32 s24, s24, 29
	v_mfma_f32_16x16x32_bf16 v[96:99], v[134:137], v[234:237], 0
	v_mfma_f32_16x16x32_bf16 v[96:99], v[138:141], v[242:245], v[96:99]
	s_add_i32 s24, s26, s24
	s_ashr_i32 s25, s24, 3
	s_and_b32 s24, s24, -8
	s_sub_i32 s24, s26, s24
	s_cmp_lt_i32 s24, 0
	v_mfma_f32_16x16x32_bf16 v[80:83], v[134:137], v[238:241], 0
	v_mfma_f32_16x16x32_bf16 v[80:83], v[138:141], v[246:249], v[80:83]
	s_movk_i32 s26, 0xb1
	s_cselect_b32 s26, s26, 0xb0
	s_mul_i32 s24, s24, s26
	s_add_i32 s24, s24, s25
	s_mul_hi_i32 s25, s24, 0x2e8ba2e9
	v_mfma_f32_16x16x32_bf16 v[76:79], v[142:145], v[238:241], 0
	v_mfma_f32_16x16x32_bf16 v[76:79], v[146:149], v[246:249], v[76:79]
	s_lshr_b32 s26, s25, 31
	s_ashr_i32 s25, s25, 5
	s_add_i32 s25, s25, s26
	s_lshl_b32 s26, s25, 3
	s_sub_i32 s27, 64, s26
	v_mfma_f32_16x16x32_bf16 v[92:95], v[142:145], v[234:237], 0
	v_mfma_f32_16x16x32_bf16 v[92:95], v[146:149], v[242:245], v[92:95]
	s_min_i32 s27, s27, 8
	s_abs_i32 s28, s27
	v_cvt_f32_u32_e32 v255, s28
	s_sub_i32 s34, 0, s28
	s_mulk_i32 s25, 0xb0
	v_mfma_f32_16x16x32_bf16 v[108:111], v[142:145], v[222:225], 0
	v_mfma_f32_16x16x32_bf16 v[108:111], v[146:149], v[230:233], v[108:111]
	s_sub_i32 s24, s24, s25
	v_rcp_iflag_f32_e32 v255, v255
	s_abs_i32 s25, s24
	s_xor_b32 s29, s24, s27
	s_ashr_i32 s29, s29, 31
	v_mfma_f32_16x16x32_bf16 v[124:127], v[142:145], v[218:221], 0
	v_mfma_f32_16x16x32_bf16 v[124:127], v[146:149], v[226:229], v[124:127]
	v_mul_f32_e32 v255, 0x4f7ffffe, v255
	v_cvt_u32_f32_e32 v255, v255
	s_nop 0
	v_readfirstlane_b32 s35, v255
	s_mul_i32 s34, s34, s35
	v_mfma_f32_16x16x32_bf16 v[120:123], v[150:153], v[218:221], 0
	v_mfma_f32_16x16x32_bf16 v[120:123], v[174:177], v[226:229], v[120:123]
	s_mul_hi_u32 s34, s35, s34
	s_add_i32 s35, s35, s34
	s_mul_hi_u32 s34, s25, s35
	s_mul_i32 s35, s34, s28
	s_sub_i32 s25, s25, s35
	v_mfma_f32_16x16x32_bf16 v[104:107], v[150:153], v[222:225], 0
	v_mfma_f32_16x16x32_bf16 v[104:107], v[174:177], v[230:233], v[104:107]
	s_add_i32 s38, s34, 1
	s_sub_i32 s35, s25, s28
	s_cmp_ge_u32 s25, s28
	s_cselect_b32 s34, s38, s34
	s_cselect_b32 s25, s35, s25
	v_mfma_f32_16x16x32_bf16 v[88:91], v[150:153], v[234:237], 0
	v_mfma_f32_16x16x32_bf16 v[88:91], v[174:177], v[242:245], v[88:91]
	s_add_i32 s35, s34, 1
	s_cmp_ge_u32 s25, s28
	s_cselect_b32 s25, s35, s34
	s_xor_b32 s25, s25, s29
	s_sub_i32 s28, s25, s29
	v_mfma_f32_16x16x32_bf16 v[72:75], v[150:153], v[238:241], 0
	v_mfma_f32_16x16x32_bf16 v[72:75], v[174:177], v[246:249], v[72:75]
	s_mul_i32 s25, s28, s27
	s_sub_i32 s24, s24, s25
	s_add_i32 s66, s26, s24
	s_mov_b32 s100, s66
	s_ashr_i32 s101, s66, 31
	v_mfma_f32_16x16x32_bf16 v[68:71], v[178:181], v[238:241], 0
	v_mfma_f32_16x16x32_bf16 v[68:71], v[182:185], v[246:249], v[68:71]
	s_lshl_b64 s[26:27], s[100:101], 19
	s_add_u32 s26, s40, s26
	s_addc_u32 s27, s41, s27
	s_and_b64 s[34:35], s[8:9], exec
	s_cselect_b32 s34, s27, s5
	v_mfma_f32_16x16x32_bf16 v[84:87], v[178:181], v[234:237], 0
	v_mfma_f32_16x16x32_bf16 v[84:87], v[182:185], v[242:245], v[84:87]
	s_cselect_b32 s35, s26, s4
	s_ashr_i32 s29, s28, 31
	s_lshl_b64 s[100:101], s[28:29], 19
	s_add_u32 s62, s10, s100
	s_addc_u32 s63, s11, s101
	v_mfma_f32_16x16x32_bf16 v[100:103], v[178:181], v[222:225], 0
	v_mfma_f32_16x16x32_bf16 v[100:103], v[182:185], v[230:233], v[100:103]
	s_and_b64 s[100:101], s[8:9], exec
	s_cselect_b32 s29, s63, s83
	s_cselect_b32 s38, s62, s82
	v_mfma_f32_16x16x32_bf16 v[116:119], v[178:181], v[218:221], 0
	v_mfma_f32_16x16x32_bf16 v[116:119], v[182:185], v[226:229], v[116:119]
	s_barrier
	s_add_i32 s24, s1, s77
	v_lshl_add_u64 v[154:155], s[86:87], 0, v[158:159]
	s_mov_b32 m0, s24
	ds_read_b128 v[218:221], v207 offset:16384
	ds_read_b128 v[222:225], v207 offset:18432
	ds_read_b128 v[226:229], v208 offset:16384
	ds_read_b128 v[230:233], v208 offset:18432
	ds_read_b128 v[234:237], v207 offset:20480
	ds_read_b128 v[238:241], v207 offset:22528
	ds_read_b128 v[242:245], v208 offset:20480
	ds_read_b128 v[246:249], v208 offset:22528
	global_load_lds_dwordx4 v[154:155], off
	v_lshl_add_u64 v[250:251], v[154:155], 0, s[14:15]
	s_add_i32 m0, s24, 0x2000
	s_add_i32 s24, s12, s77
	global_load_lds_dwordx4 v[250:251], off
	v_lshl_add_u64 v[250:251], v[154:155], 0, s[16:17]
	s_mov_b32 m0, s24
	s_nop 0
	global_load_lds_dwordx4 v[250:251], off
	v_lshl_add_u64 v[250:251], v[154:155], 0, s[18:19]
	s_add_i32 m0, s24, 0x2000
	s_nop 0
	global_load_lds_dwordx4 v[250:251], off
	s_waitcnt vmcnt(4)
	s_waitcnt lgkmcnt(0)
	s_barrier
	v_mfma_f32_16x16x32_bf16 v[64:67], v[134:137], v[218:221], 0
	v_mfma_f32_16x16x32_bf16 v[64:67], v[138:141], v[226:229], v[64:67]
	v_mfma_f32_16x16x32_bf16 v[48:51], v[134:137], v[222:225], 0
	v_mfma_f32_16x16x32_bf16 v[48:51], v[138:141], v[230:233], v[48:51]
	v_mfma_f32_16x16x32_bf16 v[32:35], v[134:137], v[234:237], 0
	v_mfma_f32_16x16x32_bf16 v[32:35], v[138:141], v[242:245], v[32:35]
	v_mfma_f32_16x16x32_bf16 v[16:19], v[134:137], v[238:241], 0
	v_mfma_f32_16x16x32_bf16 v[16:19], v[138:141], v[246:249], v[16:19]
	v_mfma_f32_16x16x32_bf16 v[12:15], v[142:145], v[238:241], 0
	v_mfma_f32_16x16x32_bf16 v[12:15], v[146:149], v[246:249], v[12:15]
	v_mfma_f32_16x16x32_bf16 v[28:31], v[142:145], v[234:237], 0
	v_mfma_f32_16x16x32_bf16 v[28:31], v[146:149], v[242:245], v[28:31]
	v_mfma_f32_16x16x32_bf16 v[44:47], v[142:145], v[222:225], 0
	v_mfma_f32_16x16x32_bf16 v[44:47], v[146:149], v[230:233], v[44:47]
	v_mfma_f32_16x16x32_bf16 v[60:63], v[142:145], v[218:221], 0
	v_mfma_f32_16x16x32_bf16 v[60:63], v[146:149], v[226:229], v[60:63]
	v_mfma_f32_16x16x32_bf16 v[56:59], v[150:153], v[218:221], 0
	v_mfma_f32_16x16x32_bf16 v[56:59], v[174:177], v[226:229], v[56:59]
	v_mfma_f32_16x16x32_bf16 v[40:43], v[150:153], v[222:225], 0
	v_mfma_f32_16x16x32_bf16 v[40:43], v[174:177], v[230:233], v[40:43]
	v_mfma_f32_16x16x32_bf16 v[24:27], v[150:153], v[234:237], 0
	v_mfma_f32_16x16x32_bf16 v[24:27], v[174:177], v[242:245], v[24:27]
	v_mfma_f32_16x16x32_bf16 v[8:11], v[150:153], v[238:241], 0
	v_mfma_f32_16x16x32_bf16 v[8:11], v[174:177], v[246:249], v[8:11]
	v_mfma_f32_16x16x32_bf16 v[4:7], v[178:181], v[238:241], 0
	v_mfma_f32_16x16x32_bf16 v[4:7], v[182:185], v[246:249], v[4:7]
	v_mfma_f32_16x16x32_bf16 v[20:23], v[178:181], v[234:237], 0
	v_mfma_f32_16x16x32_bf16 v[20:23], v[182:185], v[242:245], v[20:23]
	v_mfma_f32_16x16x32_bf16 v[36:39], v[178:181], v[222:225], 0
	v_mfma_f32_16x16x32_bf16 v[36:39], v[182:185], v[230:233], v[36:39]
	v_mfma_f32_16x16x32_bf16 v[52:55], v[178:181], v[218:221], 0
	v_mfma_f32_16x16x32_bf16 v[52:55], v[182:185], v[226:229], v[52:55]
	s_barrier
	ds_read_b128 v[134:137], v213
	ds_read_b128 v[138:141], v214
	ds_read_b128 v[142:145], v209
	ds_read_b128 v[146:149], v210
	ds_read_b128 v[150:153], v215
	ds_read_b128 v[174:177], v216
	ds_read_b128 v[178:181], v211
	ds_read_b128 v[182:185], v212
	s_mov_b32 m0, s79
	v_lshl_add_u64 v[250:251], s[82:83], 0, v[0:1]
	ds_read_b128 v[218:221], v207 offset:32768
	ds_read_b128 v[222:225], v207 offset:34816
	ds_read_b128 v[226:229], v208 offset:32768
	ds_read_b128 v[230:233], v208 offset:34816
	ds_read_b128 v[234:237], v207 offset:36864
	ds_read_b128 v[238:241], v207 offset:38912
	ds_read_b128 v[242:245], v208 offset:36864
	ds_read_b128 v[246:249], v208 offset:38912
	global_load_lds_dwordx4 v[250:251], off
	v_lshl_add_u64 v[252:253], v[250:251], 0, s[20:21]
	s_mov_b32 m0, s81
	s_nop 0
	global_load_lds_dwordx4 v[252:253], off
	v_lshl_add_u64 v[252:253], v[250:251], 0, s[14:15]
	s_mov_b32 m0, s97
	v_lshl_add_u64 v[250:251], v[250:251], 0, s[22:23]
	global_load_lds_dwordx4 v[252:253], off
	s_mov_b32 m0, s64
	s_nop 0
	global_load_lds_dwordx4 v[250:251], off
	s_waitcnt vmcnt(8)
	s_waitcnt lgkmcnt(0)
	s_barrier
	v_mfma_f32_16x16x32_bf16 v[128:131], v[134:137], v[218:221], v[128:131]
	v_mfma_f32_16x16x32_bf16 v[128:131], v[138:141], v[226:229], v[128:131]
	v_mfma_f32_16x16x32_bf16 v[112:115], v[138:141], v[230:233], v[112:115]
	v_mfma_f32_16x16x32_bf16 v[112:115], v[134:137], v[222:225], v[112:115]
	v_mfma_f32_16x16x32_bf16 v[96:99], v[134:137], v[234:237], v[96:99]
	v_mfma_f32_16x16x32_bf16 v[96:99], v[138:141], v[242:245], v[96:99]
	v_mfma_f32_16x16x32_bf16 v[80:83], v[138:141], v[246:249], v[80:83]
	v_mfma_f32_16x16x32_bf16 v[80:83], v[134:137], v[238:241], v[80:83]
	v_mfma_f32_16x16x32_bf16 v[76:79], v[142:145], v[238:241], v[76:79]
	v_mfma_f32_16x16x32_bf16 v[76:79], v[146:149], v[246:249], v[76:79]
	v_mfma_f32_16x16x32_bf16 v[92:95], v[146:149], v[242:245], v[92:95]
	v_mfma_f32_16x16x32_bf16 v[92:95], v[142:145], v[234:237], v[92:95]
	v_mfma_f32_16x16x32_bf16 v[108:111], v[142:145], v[222:225], v[108:111]
	v_mfma_f32_16x16x32_bf16 v[108:111], v[146:149], v[230:233], v[108:111]
	v_mfma_f32_16x16x32_bf16 v[124:127], v[146:149], v[226:229], v[124:127]
	v_mfma_f32_16x16x32_bf16 v[124:127], v[142:145], v[218:221], v[124:127]
	v_mfma_f32_16x16x32_bf16 v[120:123], v[150:153], v[218:221], v[120:123]
	v_mfma_f32_16x16x32_bf16 v[120:123], v[174:177], v[226:229], v[120:123]
	v_mfma_f32_16x16x32_bf16 v[104:107], v[174:177], v[230:233], v[104:107]
	v_mfma_f32_16x16x32_bf16 v[104:107], v[150:153], v[222:225], v[104:107]
	v_mfma_f32_16x16x32_bf16 v[88:91], v[150:153], v[234:237], v[88:91]
	v_mfma_f32_16x16x32_bf16 v[88:91], v[174:177], v[242:245], v[88:91]
	v_mfma_f32_16x16x32_bf16 v[72:75], v[174:177], v[246:249], v[72:75]
	v_mfma_f32_16x16x32_bf16 v[72:75], v[150:153], v[238:241], v[72:75]
	v_mfma_f32_16x16x32_bf16 v[68:71], v[178:181], v[238:241], v[68:71]
	v_mfma_f32_16x16x32_bf16 v[68:71], v[182:185], v[246:249], v[68:71]
	v_mfma_f32_16x16x32_bf16 v[84:87], v[182:185], v[242:245], v[84:87]
	v_mfma_f32_16x16x32_bf16 v[84:87], v[178:181], v[234:237], v[84:87]
	v_mfma_f32_16x16x32_bf16 v[100:103], v[178:181], v[222:225], v[100:103]
	v_mfma_f32_16x16x32_bf16 v[100:103], v[182:185], v[230:233], v[100:103]
	v_mfma_f32_16x16x32_bf16 v[116:119], v[182:185], v[226:229], v[116:119]
	v_mfma_f32_16x16x32_bf16 v[116:119], v[178:181], v[218:221], v[116:119]
	s_barrier
	s_add_i32 s24, s70, s77
	v_lshl_add_u64 v[250:251], v[154:155], 0, s[48:49]
	s_mov_b32 m0, s24
	ds_read_b128 v[218:221], v207 offset:49152
	ds_read_b128 v[222:225], v207 offset:51200
	ds_read_b128 v[226:229], v208 offset:49152
	ds_read_b128 v[230:233], v208 offset:51200
	ds_read_b128 v[234:237], v207 offset:53248
	ds_read_b128 v[238:241], v207 offset:55296
	ds_read_b128 v[242:245], v208 offset:53248
	ds_read_b128 v[246:249], v208 offset:55296
	global_load_lds_dwordx4 v[250:251], off
	v_lshl_add_u64 v[250:251], v[154:155], 0, s[50:51]
	s_add_i32 m0, s24, 0x2000
	s_add_i32 s24, s71, s77
	global_load_lds_dwordx4 v[250:251], off
	v_lshl_add_u64 v[250:251], v[154:155], 0, s[52:53]
	s_mov_b32 m0, s24
	v_lshl_add_u64 v[154:155], v[154:155], 0, s[54:55]
	global_load_lds_dwordx4 v[250:251], off
	s_add_i32 m0, s24, 0x2000
	s_nop 0
	global_load_lds_dwordx4 v[154:155], off
	s_waitcnt vmcnt(4)
	s_waitcnt lgkmcnt(0)
	s_barrier
	v_mfma_f32_16x16x32_bf16 v[64:67], v[134:137], v[218:221], v[64:67]
	v_mfma_f32_16x16x32_bf16 v[64:67], v[138:141], v[226:229], v[64:67]
	v_mfma_f32_16x16x32_bf16 v[48:51], v[138:141], v[230:233], v[48:51]
	v_mfma_f32_16x16x32_bf16 v[48:51], v[134:137], v[222:225], v[48:51]
	v_mfma_f32_16x16x32_bf16 v[32:35], v[134:137], v[234:237], v[32:35]
	v_mfma_f32_16x16x32_bf16 v[32:35], v[138:141], v[242:245], v[32:35]
	v_mfma_f32_16x16x32_bf16 v[16:19], v[138:141], v[246:249], v[16:19]
	v_mfma_f32_16x16x32_bf16 v[16:19], v[134:137], v[238:241], v[16:19]
	v_mfma_f32_16x16x32_bf16 v[12:15], v[142:145], v[238:241], v[12:15]
	v_mfma_f32_16x16x32_bf16 v[12:15], v[146:149], v[246:249], v[12:15]
	v_mfma_f32_16x16x32_bf16 v[28:31], v[146:149], v[242:245], v[28:31]
	v_mfma_f32_16x16x32_bf16 v[28:31], v[142:145], v[234:237], v[28:31]
	v_mfma_f32_16x16x32_bf16 v[44:47], v[142:145], v[222:225], v[44:47]
	v_mfma_f32_16x16x32_bf16 v[44:47], v[146:149], v[230:233], v[44:47]
	v_mfma_f32_16x16x32_bf16 v[60:63], v[146:149], v[226:229], v[60:63]
	v_mfma_f32_16x16x32_bf16 v[60:63], v[142:145], v[218:221], v[60:63]
	v_mfma_f32_16x16x32_bf16 v[56:59], v[150:153], v[218:221], v[56:59]
	v_mfma_f32_16x16x32_bf16 v[56:59], v[174:177], v[226:229], v[56:59]
	v_mfma_f32_16x16x32_bf16 v[40:43], v[174:177], v[230:233], v[40:43]
	v_mfma_f32_16x16x32_bf16 v[40:43], v[150:153], v[222:225], v[40:43]
	v_mfma_f32_16x16x32_bf16 v[24:27], v[150:153], v[234:237], v[24:27]
	v_mfma_f32_16x16x32_bf16 v[24:27], v[174:177], v[242:245], v[24:27]
	v_mfma_f32_16x16x32_bf16 v[8:11], v[174:177], v[246:249], v[8:11]
	v_mfma_f32_16x16x32_bf16 v[8:11], v[150:153], v[238:241], v[8:11]
	v_mfma_f32_16x16x32_bf16 v[4:7], v[178:181], v[238:241], v[4:7]
	v_mfma_f32_16x16x32_bf16 v[4:7], v[182:185], v[246:249], v[4:7]
	v_mfma_f32_16x16x32_bf16 v[20:23], v[182:185], v[242:245], v[20:23]
	v_mfma_f32_16x16x32_bf16 v[20:23], v[178:181], v[234:237], v[20:23]
	v_mfma_f32_16x16x32_bf16 v[36:39], v[178:181], v[222:225], v[36:39]
	v_mfma_f32_16x16x32_bf16 v[36:39], v[182:185], v[230:233], v[36:39]
	v_mfma_f32_16x16x32_bf16 v[52:55], v[182:185], v[226:229], v[52:55]
	v_mfma_f32_16x16x32_bf16 v[52:55], v[178:181], v[218:221], v[52:55]
	s_barrier
	s_add_i32 s94, s94, 2
	s_add_u32 vcc_lo, vcc_lo, 0x100
	s_addc_u32 vcc_hi, vcc_hi, 0
	s_cmp_gt_u32 s94, 13
